# norm phase: the deferred modulation units run on workgroups 128..255 instead of 0..127, so the workgroups that also own the sample rows' third row iteration no longer carry both, on top of v9
# speedup vs baseline: 1.0084x; 1.0033x over previous
.LBB0_666:
	s_and_b64 vcc, exec, s[0:1]
	s_cbranch_vccz .LBB0_680
	v_readlane_b32 s0, v251, 37
	v_readlane_b32 s1, v251, 38
	s_and_b64 s[0:1], s[0:1], exec
	v_readlane_b32 s0, v251, 54
	s_cselect_b32 s14, 0, s0
	v_readlane_b32 s20, v252, 4
	s_or_b32 s0, s20, s14
	s_cmp_lg_u32 s0, 0
	s_cselect_b64 s[4:5], -1, 0
	s_and_b64 vcc, exec, s[4:5]
	v_readlane_b32 s1, v251, 55
	s_cbranch_vccnz .LBB0_712
	s_cmpk_lg_i32 s41, 0x100
	s_cbranch_scc1 .LBB0_706
	s_ashr_i32 s0, s35, 3
	s_cmp_lt_i32 s0, 16
	s_cbranch_scc1 .LBB0_706
	s_sub_i32 s0, s0, 16
	s_lshl_b32 s1, s35, 4
	s_and_b32 s1, s1, 0x70
	s_add_i32 s0, s1, s0
	s_cmp_lt_i32 s0, 64
	s_cselect_b32 s1, 32, 64
	s_add_i32 s0, s0, s1
	s_addk_i32 s0, 0xc0
	s_mul_hi_i32 s1, s0, 0x2aaaaaab
	s_lshr_b32 s2, s1, 31
	s_ashr_i32 s1, s1, 5
	s_add_i32 s15, s1, s2
	s_mul_i32 s1, s15, 0xc0
	s_sub_i32 s6, s0, s1
	v_readlane_b32 s0, v252, 0
	v_readlane_b32 s1, v252, 1
	s_lshl_b64 s[0:1], s[0:1], 3
	s_add_u32 s2, s94, s0
	s_addc_u32 s3, s95, s1
	s_load_dwordx2 s[0:1], s[2:3], 0x48
	v_readlane_b32 s12, v251, 59
	s_mul_i32 s8, s15, 0x1800000
	s_lshl_b32 s6, s6, 5
	s_lshl_b32 s16, s12, 7
	s_mul_hi_i32 s7, s15, 0x1800000
	s_waitcnt lgkmcnt(0)
	s_add_u32 s0, s0, s8
	s_addc_u32 s1, s1, s7
	v_readlane_b32 s8, v251, 57
	v_readlane_b32 s9, v251, 58
	s_add_u32 s10, s8, 0x110000
	s_addc_u32 s11, s9, 0
	s_lshl_b32 s7, s12, 14
	s_add_i32 s12, s7, 0
	s_ashr_i32 s7, s6, 31
	s_lshl_b64 s[8:9], s[6:7], 2
	v_and_b32_e32 v160, 31, v214
	s_add_u32 s0, s0, s8
	s_addc_u32 s1, s1, s9
	v_lshlrev_b32_e32 v208, 2, v160
	v_lshlrev_b32_e32 v0, 4, v235
	v_lshl_add_u64 v[162:163], s[0:1], 0, v[208:209]
	v_and_b32_e32 v208, 0x70, v0
	v_lshrrev_b32_e32 v161, 5, v235
	v_lshl_add_u64 v[0:1], s[10:11], 0, v[208:209]
	v_lshlrev_b32_e32 v208, 11, v160
	v_lshrrev_b32_e32 v4, 3, v235
	v_lshl_add_u64 v[2:3], s[10:11], 0, v[208:209]
	v_lshlrev_b32_e32 v208, 4, v161
	v_lshl_add_u64 v[164:165], v[2:3], 0, v[208:209]
	v_xor_b32_e32 v3, v4, v235
	v_and_b32_e32 v5, 7, v214
	v_lshl_add_u32 v2, v4, 7, s12
	v_lshlrev_b32_e32 v3, 4, v3
	v_bitop3_b32 v6, v161, v5, 6 bitop3:0x36
	v_mov_b32_e32 v7, 0xfffff000
	v_lshlrev_b32_e32 v208, 11, v4
	v_bitop3_b32 v4, v161, v214, 7 bitop3:0x78
	s_waitcnt vmcnt(0)
	v_bitop3_b32 v8, v161, v5, 2 bitop3:0x36
	v_bitop3_b32 v5, v161, v5, 4 bitop3:0x36
	v_and_b32_e32 v3, 0x70, v3
	v_lshl_add_u32 v6, v6, 4, s12
	v_lshl_or_b32 v7, v235, 7, v7
	v_lshl_add_u32 v4, v4, 4, s12
	v_lshl_add_u32 v8, v8, 4, s12
	v_lshl_add_u32 v5, v5, 4, s12
	v_mov_b32_e32 v48, 0
	v_lshlrev_b32_e32 v170, 3, v161
	v_cmp_gt_u32_e64 s[0:1], 4, v160
	v_lshl_add_u64 v[166:167], v[0:1], 0, v[208:209]
	s_mov_b32 s7, 0
	s_mov_b64 s[10:11], -1
	v_add_u32_e32 v171, v2, v3
	v_add_u32_e32 v172, v4, v7
	v_add_u32_e32 v173, v8, v7
	v_add_u32_e32 v174, v5, v7
	v_add_u32_e32 v175, v6, v7
	v_mov_b32_e32 v49, v48
	v_mov_b32_e32 v50, v48
	v_mov_b32_e32 v51, v48
	v_mov_b32_e32 v52, v48
	v_mov_b32_e32 v53, v48
	v_mov_b32_e32 v54, v48
	v_mov_b32_e32 v55, v48
	v_mov_b32_e32 v56, v48
	v_mov_b32_e32 v57, v48
	v_mov_b32_e32 v58, v48
	v_mov_b32_e32 v59, v48
	v_mov_b32_e32 v60, v48
	v_mov_b32_e32 v61, v48
	v_mov_b32_e32 v62, v48
	v_mov_b32_e32 v63, v48
	v_mov_b32_e32 v32, v48
	v_mov_b32_e32 v33, v48
	v_mov_b32_e32 v34, v48
	v_mov_b32_e32 v35, v48
	v_mov_b32_e32 v36, v48
	v_mov_b32_e32 v37, v48
	v_mov_b32_e32 v38, v48
	v_mov_b32_e32 v39, v48
	v_mov_b32_e32 v40, v48
	v_mov_b32_e32 v41, v48
	v_mov_b32_e32 v42, v48
	v_mov_b32_e32 v43, v48
	v_mov_b32_e32 v44, v48
	v_mov_b32_e32 v45, v48
	v_mov_b32_e32 v46, v48
	v_mov_b32_e32 v47, v48
	v_mov_b32_e32 v16, v48
	v_mov_b32_e32 v17, v48
	v_mov_b32_e32 v18, v48
	v_mov_b32_e32 v19, v48
	v_mov_b32_e32 v20, v48
	v_mov_b32_e32 v21, v48
	v_mov_b32_e32 v22, v48
	v_mov_b32_e32 v23, v48
	v_mov_b32_e32 v24, v48
	v_mov_b32_e32 v25, v48
	v_mov_b32_e32 v26, v48
	v_mov_b32_e32 v27, v48
	v_mov_b32_e32 v28, v48
	v_mov_b32_e32 v29, v48
	v_mov_b32_e32 v30, v48
	v_mov_b32_e32 v31, v48
	v_mov_b32_e32 v0, v48
	v_mov_b32_e32 v1, v48
	v_mov_b32_e32 v2, v48
	v_mov_b32_e32 v3, v48
	v_mov_b32_e32 v4, v48
	v_mov_b32_e32 v5, v48
	v_mov_b32_e32 v6, v48
	v_mov_b32_e32 v7, v48
	v_mov_b32_e32 v8, v48
	v_mov_b32_e32 v9, v48
	v_mov_b32_e32 v10, v48
	v_mov_b32_e32 v11, v48
	v_mov_b32_e32 v12, v48
	v_mov_b32_e32 v13, v48
	v_mov_b32_e32 v14, v48
	v_mov_b32_e32 v15, v48
	v_mov_b32_e32 v64, v48
	v_mov_b32_e32 v65, v48
	v_mov_b32_e32 v66, v48
	v_mov_b32_e32 v67, v48
	v_mov_b32_e32 v68, v48
	v_mov_b32_e32 v69, v48
	v_mov_b32_e32 v70, v48
	v_mov_b32_e32 v71, v48
	v_mov_b32_e32 v72, v48
	v_mov_b32_e32 v73, v48
	v_mov_b32_e32 v74, v48
	v_mov_b32_e32 v75, v48
	v_mov_b32_e32 v76, v48
	v_mov_b32_e32 v77, v48
	v_mov_b32_e32 v78, v48
	v_mov_b32_e32 v79, v48
	s_barrier
	s_branch .LBB0_672
